# P1 weight-quantisation tile loads also nt
# speedup vs baseline: 1.0410x; 1.0026x over previous
.LBB0_184:
	s_cmpk_gt_i32 s92, 0xbf
	s_mov_b64 s[4:5], -1
	s_cbranch_scc0 .LBB0_191
	s_lshl_b32 s4, s3, 4
	s_and_b32 s21, s4, 0xffffff00
	s_mov_b64 s[4:5], s[0:1]
	s_add_i32 s6, s92, 0xffffff40
	s_load_dwordx2 s[10:11], s[4:5], 0x80
	s_lshl_b32 s4, s92, 6
	s_and_b32 s20, s4, 0x3c0
	s_lshr_b32 s4, s6, 1
	s_and_b32 s24, s4, 0x7fffff8
	s_mov_b64 s[4:5], s[0:1]
	s_mov_b64 s[6:7], s[0:1]
	s_load_dwordx2 s[4:5], s[4:5], 0xa0
	s_load_dwordx2 s[6:7], s[6:7], 0xa0
	s_mov_b64 s[18:19], s[0:1]
	s_load_dwordx2 s[18:19], s[18:19], 0xa0
	s_add_i32 s24, s24, s8
	s_lshl_b32 s24, s24, 5
	s_waitcnt lgkmcnt(0)
	s_add_u32 s6, s6, 0xac000
	s_addc_u32 s7, s7, 0
	s_add_u32 s18, s18, 0x548000
	s_addc_u32 s19, s19, 0
	s_ashr_i32 s25, s24, 31
	s_lshl_b64 s[24:25], s[24:25], 2
	v_or_b32_e32 v8, s20, v1
	s_add_u32 s10, s10, s24
	s_addc_u32 s11, s11, s25
	v_mul_u32_u24_e32 v8, 0x1600, v8
	v_lshl_add_u64 v[6:7], s[10:11], 0, v[2:3]
	v_lshlrev_b32_e32 v8, 2, v8
	v_mov_b32_e32 v9, v3
	v_lshl_add_u64 v[6:7], v[6:7], 0, v[8:9]
	s_mov_b32 s10, 0xb000
	v_add_co_u32_e32 v8, vcc, s10, v6
	s_mov_b32 s10, 0x16000
	s_nop 0
	v_addc_co_u32_e32 v9, vcc, 0, v7, vcc
	v_add_co_u32_e32 v10, vcc, s10, v6
	s_mov_b32 s10, 0x21000
	s_nop 0
	v_addc_co_u32_e32 v11, vcc, 0, v7, vcc
	v_add_co_u32_e32 v12, vcc, s10, v6
	s_mov_b32 s10, 0x2c000
	s_nop 0
	v_addc_co_u32_e32 v13, vcc, 0, v7, vcc
	v_add_co_u32_e32 v14, vcc, s10, v6
	s_mov_b32 s10, 0x37000
	s_nop 0
	v_addc_co_u32_e32 v15, vcc, 0, v7, vcc
	v_add_co_u32_e32 v16, vcc, s10, v6
	s_mov_b32 s10, 0x42000
	s_nop 0
	v_addc_co_u32_e32 v17, vcc, 0, v7, vcc
	v_add_co_u32_e32 v18, vcc, s10, v6
	s_mov_b32 s10, 0x4d000
	s_nop 0
	v_addc_co_u32_e32 v19, vcc, 0, v7, vcc
	v_add_co_u32_e32 v38, vcc, s10, v6
	s_mov_b32 s10, 0x58000
	s_nop 0
	v_addc_co_u32_e32 v39, vcc, 0, v7, vcc
	global_load_dword v37, v[6:7], off nt
	global_load_dword v42, v[8:9], off nt
	global_load_dword v43, v[10:11], off nt
	global_load_dword v44, v[12:13], off nt
	global_load_dword v45, v[14:15], off nt
	global_load_dword v46, v[16:17], off nt
	global_load_dword v47, v[18:19], off nt
	global_load_dword v48, v[38:39], off nt
	v_add_co_u32_e32 v8, vcc, s10, v6
	s_add_u32 s4, s4, s20
	s_nop 0
	v_addc_co_u32_e32 v9, vcc, 0, v7, vcc
	v_add_co_u32_e32 v10, vcc, s16, v6
	s_addc_u32 s5, s5, 0
	s_nop 0
	v_addc_co_u32_e32 v11, vcc, 0, v7, vcc
	v_add_co_u32_e32 v12, vcc, s17, v6
	s_mov_b32 s24, 0
	s_nop 0
	v_addc_co_u32_e32 v13, vcc, 0, v7, vcc
	v_add_co_u32_e32 v14, vcc, s23, v6
	s_mov_b32 s25, 16
	s_nop 0
	v_addc_co_u32_e32 v15, vcc, 0, v7, vcc
	v_add_co_u32_e32 v16, vcc, s33, v6
	s_nop 1
	v_addc_co_u32_e32 v17, vcc, 0, v7, vcc
	v_add_co_u32_e32 v18, vcc, s36, v6
	s_nop 1
	v_addc_co_u32_e32 v19, vcc, 0, v7, vcc
	v_add_co_u32_e32 v38, vcc, s37, v6
	s_nop 1
	v_addc_co_u32_e32 v39, vcc, 0, v7, vcc
	v_add_co_u32_e32 v40, vcc, s38, v6
	s_nop 1
	v_addc_co_u32_e32 v41, vcc, 0, v7, vcc
	global_load_dword v49, v[8:9], off nt
	global_load_dword v50, v[10:11], off nt
	global_load_dword v51, v[12:13], off nt
	global_load_dword v52, v[14:15], off nt
	global_load_dword v53, v[16:17], off nt
	global_load_dword v54, v[18:19], off nt
	global_load_dword v55, v[38:39], off nt
	global_load_dword v56, v[40:41], off nt
	v_add_co_u32_e32 v8, vcc, s39, v6
	s_nop 1
	v_addc_co_u32_e32 v9, vcc, 0, v7, vcc
	v_add_co_u32_e32 v10, vcc, s40, v6
	s_nop 1
	v_addc_co_u32_e32 v11, vcc, 0, v7, vcc
	v_add_co_u32_e32 v12, vcc, s41, v6
	s_nop 1
	v_addc_co_u32_e32 v13, vcc, 0, v7, vcc
	v_add_co_u32_e32 v14, vcc, s42, v6
	s_nop 1
	v_addc_co_u32_e32 v15, vcc, 0, v7, vcc
	v_add_co_u32_e32 v16, vcc, s43, v6
	s_nop 1
	v_addc_co_u32_e32 v17, vcc, 0, v7, vcc
	v_add_co_u32_e32 v18, vcc, s44, v6
	s_nop 1
	v_addc_co_u32_e32 v19, vcc, 0, v7, vcc
	v_add_co_u32_e32 v38, vcc, s45, v6
	s_nop 1
	v_addc_co_u32_e32 v39, vcc, 0, v7, vcc
	v_add_co_u32_e32 v40, vcc, s46, v6
	s_nop 1
	v_addc_co_u32_e32 v41, vcc, 0, v7, vcc
	global_load_dword v57, v[8:9], off nt
	global_load_dword v58, v[10:11], off nt
	global_load_dword v59, v[12:13], off nt
	global_load_dword v60, v[14:15], off nt
	global_load_dword v61, v[16:17], off nt
	global_load_dword v62, v[18:19], off nt
	global_load_dword v63, v[38:39], off nt
	s_nop 0
	global_load_dword v40, v[40:41], off nt
	v_add_co_u32_e32 v8, vcc, s47, v6
	s_nop 1
	v_addc_co_u32_e32 v9, vcc, 0, v7, vcc
	v_add_co_u32_e32 v10, vcc, s48, v6
	s_nop 1
	v_addc_co_u32_e32 v11, vcc, 0, v7, vcc
	v_add_co_u32_e32 v12, vcc, s49, v6
	s_nop 1
	v_addc_co_u32_e32 v13, vcc, 0, v7, vcc
	v_add_co_u32_e32 v14, vcc, s50, v6
	s_nop 1
	v_addc_co_u32_e32 v15, vcc, 0, v7, vcc
	v_add_co_u32_e32 v16, vcc, s51, v6
	s_nop 1
	v_addc_co_u32_e32 v17, vcc, 0, v7, vcc
	v_add_co_u32_e32 v18, vcc, s52, v6
	s_nop 1
	v_addc_co_u32_e32 v19, vcc, 0, v7, vcc
	v_add_co_u32_e32 v38, vcc, s53, v6
	s_nop 1
	v_addc_co_u32_e32 v39, vcc, 0, v7, vcc
	v_add_co_u32_e32 v6, vcc, s54, v6
	s_nop 1
	v_addc_co_u32_e32 v7, vcc, 0, v7, vcc
	global_load_dword v8, v[8:9], off nt
	s_nop 0
	global_load_dword v9, v[10:11], off nt
	s_nop 0
	global_load_dword v10, v[12:13], off nt
	global_load_dword v11, v[14:15], off nt
	s_nop 0
	global_load_dword v14, v[16:17], off nt
	global_load_dword v15, v[18:19], off nt
	s_nop 0
	global_load_dword v16, v[38:39], off nt
	s_nop 0
	global_load_dword v6, v[6:7], off nt
	s_waitcnt vmcnt(30)
	ds_write2_b32 v27, v37, v42 offset1:66
	s_waitcnt vmcnt(28)
	ds_write2_b32 v27, v43, v44 offset0:132 offset1:198
	s_waitcnt vmcnt(26)
	ds_write2_b32 v28, v45, v46 offset0:8 offset1:74
	s_waitcnt vmcnt(24)
	ds_write2_b32 v28, v47, v48 offset0:140 offset1:206
	s_waitcnt vmcnt(22)
	ds_write2_b32 v29, v49, v50 offset0:16 offset1:82
	s_waitcnt vmcnt(20)
	ds_write2_b32 v29, v51, v52 offset0:148 offset1:214
	s_waitcnt vmcnt(18)
	ds_write2_b32 v30, v53, v54 offset0:24 offset1:90
	s_waitcnt vmcnt(16)
	ds_write2_b32 v30, v55, v56 offset0:156 offset1:222
	s_waitcnt vmcnt(14)
	ds_write2_b32 v31, v57, v58 offset0:32 offset1:98
	s_waitcnt vmcnt(12)
	ds_write2_b32 v31, v59, v60 offset0:164 offset1:230
	s_waitcnt vmcnt(10)
	ds_write2_b32 v32, v61, v62 offset0:40 offset1:106
	s_waitcnt vmcnt(8)
	ds_write2_b32 v32, v63, v40 offset0:172 offset1:238
	s_waitcnt vmcnt(6)
	ds_write2_b32 v33, v8, v9 offset0:48 offset1:114
	s_waitcnt vmcnt(4)
	ds_write2_b32 v33, v10, v11 offset0:180 offset1:246
	s_waitcnt vmcnt(2)
	ds_write2_b32 v34, v14, v15 offset0:56 offset1:122
	s_waitcnt vmcnt(0)
	ds_write2_b32 v34, v16, v6 offset0:188 offset1:254
	s_waitcnt lgkmcnt(0)
	v_add_u32_e32 v13, s21, v22
	v_lshl_add_u64 v[6:7], s[4:5], 0, v[4:5]
	v_or_b32_e32 v8, s20, v20
	v_add_u32_e32 v12, s21, v23
	v_lshl_add_u64 v[6:7], v[6:7], 0, s[12:13]
	v_cmp_eq_u32_e64 s[4:5], 0, v8
	v_mov_b32_e32 v14, v24
	v_mov_b32_e32 v15, v13
	s_branch .LBB0_187

.LBB0_193:
	s_and_b32 s4, s92, 0xffffffc0
	s_cmp_eq_u32 s4, 64
	s_cselect_b32 s4, 16, 24
	s_cmp_gt_u32 s92, 63
	s_cselect_b32 s4, s4, 12
	s_bfe_u32 s5, s92, 0x20004
	s_or_b32 s20, s4, s5
	s_mov_b64 s[4:5], s[0:1]
	s_load_dwordx2 s[26:27], s[4:5], 0x28
	s_mov_b64 s[4:5], s[0:1]
	s_mov_b64 s[6:7], s[0:1]
	s_load_dwordx2 s[4:5], s[4:5], 0xa0
	s_mov_b64 s[18:19], s[0:1]
	s_load_dwordx2 s[6:7], s[6:7], 0xa0
	s_load_dwordx2 s[18:19], s[18:19], 0xa0
	s_lshl_b32 s10, s92, 6
	s_lshl_b32 s21, s20, 8
	s_and_b32 s24, s10, 0x3c0
	s_add_i32 s28, s21, s2
	s_waitcnt lgkmcnt(0)
	s_add_u32 s18, s18, 0x540000
	s_addc_u32 s19, s19, 0
	s_ashr_i32 s29, s28, 31
	s_lshl_b64 s[28:29], s[28:29], 2
	v_or_b32_e32 v8, s24, v1
	s_add_u32 s26, s26, s28
	s_addc_u32 s27, s27, s29
	v_mul_u32_u24_e32 v8, 0x1c00, v8
	v_lshl_add_u64 v[6:7], s[26:27], 0, v[2:3]
	v_lshlrev_b32_e32 v8, 2, v8
	v_mov_b32_e32 v9, v3
	v_lshl_add_u64 v[6:7], v[6:7], 0, v[8:9]
	v_add_co_u32_e32 v8, vcc, s58, v6
	s_add_u32 s4, s4, s24
	s_nop 0
	v_addc_co_u32_e32 v9, vcc, 0, v7, vcc
	v_add_co_u32_e32 v10, vcc, s59, v6
	s_addc_u32 s5, s5, 0
	s_nop 0
	v_addc_co_u32_e32 v11, vcc, 0, v7, vcc
	v_add_co_u32_e32 v12, vcc, s61, v6
	s_lshl_b32 s10, s20, 9
	s_nop 0
	v_addc_co_u32_e32 v13, vcc, 0, v7, vcc
	v_add_co_u32_e32 v14, vcc, s62, v6
	s_add_i32 s94, s9, s10
	s_nop 0
	v_addc_co_u32_e32 v15, vcc, 0, v7, vcc
	v_add_co_u32_e32 v16, vcc, s63, v6
	s_add_u32 s6, s6, 0xa4000
	s_nop 0
	v_addc_co_u32_e32 v17, vcc, 0, v7, vcc
	v_add_co_u32_e32 v18, vcc, s64, v6
	s_addc_u32 s7, s7, 0
	s_nop 0
	v_addc_co_u32_e32 v19, vcc, 0, v7, vcc
	v_add_co_u32_e32 v38, vcc, s65, v6
	s_mov_b32 s93, 0
	s_nop 0
	v_addc_co_u32_e32 v39, vcc, 0, v7, vcc
	global_load_dword v37, v[6:7], off nt
	global_load_dword v42, v[8:9], off nt
	global_load_dword v43, v[10:11], off nt
	global_load_dword v44, v[12:13], off nt
	global_load_dword v45, v[14:15], off nt
	global_load_dword v46, v[16:17], off nt
	global_load_dword v47, v[18:19], off nt
	global_load_dword v48, v[38:39], off nt
	v_add_co_u32_e32 v8, vcc, s66, v6
	s_movk_i32 s95, 0x1810
	s_nop 0
	v_addc_co_u32_e32 v9, vcc, 0, v7, vcc
	v_add_co_u32_e32 v10, vcc, s67, v6
	s_mov_b32 s96, 0
	s_nop 0
	v_addc_co_u32_e32 v11, vcc, 0, v7, vcc
	v_add_co_u32_e32 v12, vcc, s68, v6
	s_nop 1
	v_addc_co_u32_e32 v13, vcc, 0, v7, vcc
	v_add_co_u32_e32 v14, vcc, s37, v6
	s_nop 1
	v_addc_co_u32_e32 v15, vcc, 0, v7, vcc
	v_add_co_u32_e32 v16, vcc, s69, v6
	s_nop 1
	v_addc_co_u32_e32 v17, vcc, 0, v7, vcc
	v_add_co_u32_e32 v18, vcc, s70, v6
	s_nop 1
	v_addc_co_u32_e32 v19, vcc, 0, v7, vcc
	v_add_co_u32_e32 v38, vcc, s71, v6
	s_nop 1
	v_addc_co_u32_e32 v39, vcc, 0, v7, vcc
	v_add_co_u32_e32 v40, vcc, s72, v6
	s_nop 1
	v_addc_co_u32_e32 v41, vcc, 0, v7, vcc
	global_load_dword v49, v[8:9], off nt
	global_load_dword v50, v[10:11], off nt
	global_load_dword v51, v[12:13], off nt
	global_load_dword v52, v[14:15], off nt
	global_load_dword v53, v[16:17], off nt
	global_load_dword v54, v[18:19], off nt
	global_load_dword v55, v[38:39], off nt
	global_load_dword v56, v[40:41], off nt
	v_add_co_u32_e32 v8, vcc, s73, v6
	s_nop 1
	v_addc_co_u32_e32 v9, vcc, 0, v7, vcc
	v_add_co_u32_e32 v10, vcc, s74, v6
	s_nop 1
	v_addc_co_u32_e32 v11, vcc, 0, v7, vcc
	v_add_co_u32_e32 v12, vcc, s75, v6
	s_nop 1
	v_addc_co_u32_e32 v13, vcc, 0, v7, vcc
	v_add_co_u32_e32 v14, vcc, s76, v6
	s_nop 1
	v_addc_co_u32_e32 v15, vcc, 0, v7, vcc
	v_add_co_u32_e32 v16, vcc, s77, v6
	s_nop 1
	v_addc_co_u32_e32 v17, vcc, 0, v7, vcc
	v_add_co_u32_e32 v18, vcc, s78, v6
	s_nop 1
	v_addc_co_u32_e32 v19, vcc, 0, v7, vcc
	v_add_co_u32_e32 v38, vcc, s51, v6
	s_nop 1
	v_addc_co_u32_e32 v39, vcc, 0, v7, vcc
	v_add_co_u32_e32 v40, vcc, s79, v6
	s_nop 1
	v_addc_co_u32_e32 v41, vcc, 0, v7, vcc
	global_load_dword v57, v[8:9], off nt
	global_load_dword v58, v[10:11], off nt
	global_load_dword v59, v[12:13], off nt
	global_load_dword v60, v[14:15], off nt
	global_load_dword v61, v[16:17], off nt
	global_load_dword v62, v[18:19], off nt
	global_load_dword v63, v[38:39], off nt
	s_nop 0
	global_load_dword v40, v[40:41], off nt
	v_add_co_u32_e32 v8, vcc, s80, v6
	s_nop 1
	v_addc_co_u32_e32 v9, vcc, 0, v7, vcc
	v_add_co_u32_e32 v10, vcc, s81, v6
	s_nop 1
	v_addc_co_u32_e32 v11, vcc, 0, v7, vcc
	v_add_co_u32_e32 v12, vcc, s82, v6
	s_nop 1
	v_addc_co_u32_e32 v13, vcc, 0, v7, vcc
	v_add_co_u32_e32 v14, vcc, s84, v6
	s_nop 1
	v_addc_co_u32_e32 v15, vcc, 0, v7, vcc
	v_add_co_u32_e32 v16, vcc, s85, v6
	s_nop 1
	v_addc_co_u32_e32 v17, vcc, 0, v7, vcc
	v_add_co_u32_e32 v18, vcc, s86, v6
	s_nop 1
	v_addc_co_u32_e32 v19, vcc, 0, v7, vcc
	v_add_co_u32_e32 v38, vcc, s87, v6
	s_nop 1
	v_addc_co_u32_e32 v39, vcc, 0, v7, vcc
	v_add_co_u32_e32 v6, vcc, s88, v6
	s_nop 1
	v_addc_co_u32_e32 v7, vcc, 0, v7, vcc
	global_load_dword v8, v[8:9], off nt
	s_nop 0
	global_load_dword v9, v[10:11], off nt
	s_nop 0
	global_load_dword v10, v[12:13], off nt
	global_load_dword v11, v[14:15], off nt
	s_nop 0
	global_load_dword v12, v[16:17], off nt
	global_load_dword v13, v[18:19], off nt
	global_load_dword v14, v[38:39], off nt
	s_nop 0
	global_load_dword v6, v[6:7], off nt
	s_waitcnt vmcnt(30)
	ds_write2_b32 v27, v37, v42 offset1:66
	s_waitcnt vmcnt(28)
	ds_write2_b32 v27, v43, v44 offset0:132 offset1:198
	s_waitcnt vmcnt(26)
	ds_write2_b32 v28, v45, v46 offset0:8 offset1:74
	s_waitcnt vmcnt(24)
	ds_write2_b32 v28, v47, v48 offset0:140 offset1:206
	s_waitcnt vmcnt(22)
	ds_write2_b32 v29, v49, v50 offset0:16 offset1:82
	s_waitcnt vmcnt(20)
	ds_write2_b32 v29, v51, v52 offset0:148 offset1:214
	s_waitcnt vmcnt(18)
	ds_write2_b32 v30, v53, v54 offset0:24 offset1:90
	s_waitcnt vmcnt(16)
	ds_write2_b32 v30, v55, v56 offset0:156 offset1:222
	s_waitcnt vmcnt(14)
	ds_write2_b32 v31, v57, v58 offset0:32 offset1:98
	s_waitcnt vmcnt(12)
	ds_write2_b32 v31, v59, v60 offset0:164 offset1:230
	s_waitcnt vmcnt(10)
	ds_write2_b32 v32, v61, v62 offset0:40 offset1:106
	s_waitcnt vmcnt(8)
	ds_write2_b32 v32, v63, v40 offset0:172 offset1:238
	s_waitcnt vmcnt(6)
	ds_write2_b32 v33, v8, v9 offset0:48 offset1:114
	s_waitcnt vmcnt(4)
	ds_write2_b32 v33, v10, v11 offset0:180 offset1:246
	s_waitcnt vmcnt(2)
	ds_write2_b32 v34, v12, v13 offset0:56 offset1:122
	s_waitcnt vmcnt(0)
	ds_write2_b32 v34, v14, v6 offset0:188 offset1:254
	s_waitcnt lgkmcnt(0)
	v_add_u32_e32 v10, s21, v22
	v_add_u32_e32 v12, s21, v23
	v_lshl_add_u64 v[6:7], s[4:5], 0, v[4:5]
	v_or_b32_e32 v8, s24, v20
	v_ashrrev_i32_e32 v13, 31, v12
	v_ashrrev_i32_e32 v11, 31, v10
	v_lshl_add_u64 v[6:7], v[6:7], 0, s[14:15]
	v_cmp_eq_u32_e64 s[4:5], 0, v8
	v_lshl_add_u32 v8, s20, 10, v26
	v_lshl_add_u64 v[12:13], v[12:13], 2, s[6:7]
	v_lshl_add_u64 v[14:15], v[10:11], 2, s[6:7]
	s_mov_b64 s[20:21], 0
	v_mov_b32_e32 v9, v24
	s_branch .LBB0_195
